# P2 unit setup de-serialised: gate-weight fragment loads and sink load issued with the first batch
# baseline (speedup 1.0000x reference)
.LBB0_200:
	v_mov_b32_e32 v52, v228
	s_ashr_i32 s28, s0, 4
	s_and_b32 s30, s0, 15
	v_readfirstlane_b32 s4, v52
	s_ashr_i32 s8, s4, 6
	s_mul_i32 s7, s28, 0x1600000
	v_readlane_b32 s2, v254, 41
	v_writelane_b32 v255, s6, 7
	s_mul_hi_i32 s6, s28, 0x1600000
	v_readlane_b32 s3, v254, 42
	s_add_u32 s2, s2, s7
	s_addc_u32 s3, s3, s6
	s_lshl_b32 s0, s0, 4
	v_lshlrev_b32_e32 v0, 3, v52
	s_and_b32 s0, s0, 0xc0
	v_and_b32_e32 v0, 56, v0
	v_add_u32_e32 v7, 0x200, v52
	v_or_b32_e32 v2, s0, v0
	v_ashrrev_i32_e32 v1, 3, v52
	v_lshrrev_b32_e32 v7, 3, v7
	v_or_b32_e32 v4, 0x400, v2
	v_mul_lo_u32 v5, v1, s60
	v_mul_lo_u32 v7, v7, s60
	v_or_b32_e32 v2, 0x500, v2
	v_writelane_b32 v255, s0, 8
	v_add_lshl_u32 v12, v2, v5, 1
	v_add_lshl_u32 v16, v2, v7, 1
	s_lshl_b32 s34, s8, 4
	v_lshrrev_b32_e32 v2, 2, v52
	s_lshl_b32 s0, s30, 6
	v_and_or_b32 v2, v2, 14, s34
	v_writelane_b32 v255, s0, 9
	s_addk_i32 s0, 0x600
	v_add_lshl_u32 v6, v4, v5, 1
	v_add_lshl_u32 v8, v4, v7, 1
	v_mul_lo_u32 v2, v2, s60
	v_or_b32_e32 v4, s0, v0
	v_add_lshl_u32 v2, v4, v2, 1
	v_writelane_b32 v255, s0, 10
	v_lshl_add_u64 v[20:21], s[2:3], 0, v[2:3]
	s_movk_i32 s0, 0x8000
	v_add_co_u32_e32 v22, vcc, s0, v20
	global_load_dwordx4 v[4:7], v6, s[2:3]
	s_nop 0
	global_load_dwordx4 v[8:11], v8, s[2:3]
	s_nop 0
	global_load_dwordx4 v[12:15], v12, s[2:3]
	s_nop 0
	global_load_dwordx4 v[16:19], v16, s[2:3]
	v_addc_co_u32_e32 v23, vcc, -1, v21, vcc
	v_add_co_u32_e32 v24, vcc, 0xffffb000, v20
	s_nop 1
	v_addc_co_u32_e32 v25, vcc, -1, v21, vcc
	global_load_dwordx4 v[28:31], v[22:23], off offset:-1024
	s_nop 0
	global_load_dwordx4 v[24:27], v[24:25], off offset:-2048
	v_add_co_u32_e32 v22, vcc, 0xffffe000, v20
	global_load_dwordx4 v[32:35], v2, s[2:3]
	s_nop 0
	v_addc_co_u32_e32 v23, vcc, -1, v21, vcc
	v_add_co_u32_e32 v20, vcc, 0x2000, v20
	s_nop 1
	v_addc_co_u32_e32 v21, vcc, 0, v21, vcc
	global_load_dwordx4 v[36:39], v[22:23], off offset:-3072
	s_nop 0
	global_load_dwordx4 v[20:23], v[20:21], off offset:3072
	v_readlane_b32 vcc_lo, v254, 29
	v_readlane_b32 vcc_hi, v254, 30
	s_lshl_b32 s2, s30, 14
	v_lshlrev_b32_e32 v216, 6, v1
	v_ashrrev_i32_e32 v217, 31, v216
	v_lshlrev_b64 v[216:217], 2, v[216:217]
	v_lshlrev_b32_e32 v218, 2, v0
	v_mov_b32_e32 v219, 0
	v_lshl_add_u64 v[216:217], v[216:217], 0, v[218:219]
	s_add_u32 vcc_lo, vcc_lo, s2
	s_addc_u32 vcc_hi, vcc_hi, 0
	v_lshl_add_u64 v[220:221], vcc, 0, v[216:217]
	global_load_dwordx4 v[238:241], v[220:221], off
	global_load_dwordx4 v[242:245], v[220:221], off offset:16
	v_readlane_b32 vcc_lo, v254, 33
	v_readlane_b32 vcc_hi, v254, 34
	s_nop 1
	s_add_u32 vcc_lo, vcc_lo, s2
	s_addc_u32 vcc_hi, vcc_hi, 0
	v_lshl_add_u64 v[220:221], vcc, 0, v[216:217]
	global_load_dwordx4 v[246:249], v[220:221], off
	global_load_dwordx4 v[250:253], v[220:221], off offset:16
	v_readlane_b32 vcc_lo, v254, 23
	v_readlane_b32 vcc_hi, v254, 24
	s_lshl_b32 s2, s30, 2
	v_mov_b32_e32 v218, s2
	s_nop 4
	global_load_dword v236, v218, vcc
	v_cmp_gt_i32_e32 vcc, 64, v52
	s_and_saveexec_b64 s[0:1], vcc
	s_cbranch_execz .LBB0_202
	v_readlane_b32 s2, v255, 9
	v_readlane_b32 s12, v254, 23
	v_readlane_b32 s20, v254, 31
	v_add_u32_e32 v40, s2, v52
	v_ashrrev_i32_e32 v41, 31, v40
	v_lshlrev_b64 v[40:41], 2, v[40:41]
	v_readlane_b32 s21, v254, 32
	v_readlane_b32 s24, v254, 35
	v_readlane_b32 s25, v254, 36
	v_lshl_add_u64 v[48:49], s[20:21], 0, v[40:41]
	v_readlane_b32 s26, v254, 37
	v_readlane_b32 s27, v254, 38
	global_load_dword v2, v[48:49], off
	v_lshl_add_u64 v[48:49], s[24:25], 0, v[40:41]
	global_load_dword v50, v[48:49], off
	v_lshl_add_u64 v[48:49], s[26:27], 0, v[40:41]
	global_load_dword v51, v[48:49], off
	v_readlane_b32 s14, v254, 25
	v_readlane_b32 s15, v254, 26
	v_readlane_b32 s16, v254, 27
	v_readlane_b32 s17, v254, 28
	v_lshl_add_u64 v[42:43], s[14:15], 0, v[40:41]
	v_add_co_u32_e32 v44, vcc, 0x1000, v42
	v_lshl_add_u64 v[40:41], s[16:17], 0, v[40:41]
	s_nop 0
	v_addc_co_u32_e32 v45, vcc, 0, v43, vcc
	v_add_co_u32_e32 v46, vcc, 0x2000, v42
	s_mov_b32 s2, 0xbfb8aa3b
	s_nop 0
	v_addc_co_u32_e32 v47, vcc, 0, v43, vcc
	v_add_co_u32_e32 v48, vcc, 0x3000, v42
	s_mov_b32 s3, 0x42ce8ed0
	s_nop 0
	v_addc_co_u32_e32 v49, vcc, 0, v43, vcc
	global_load_dword v40, v[40:41], off
	s_nop 0
	global_load_dword v41, v[42:43], off
	s_nop 0
	global_load_dword v42, v[44:45], off
	global_load_dword v43, v[46:47], off
	s_nop 0
	global_load_dword v44, v[48:49], off
	v_lshl_add_u32 v45, v52, 2, 0
	v_add_u32_e32 v46, 0x1f000, v45
	s_mov_b32 s5, 0xc2b17218
	s_mov_b32 s9, 0x3f2aaaab
	s_mov_b32 s10, 0x3f317218
	v_readlane_b32 s13, v254, 24
	v_readlane_b32 s18, v254, 29
	v_readlane_b32 s19, v254, 30
	v_readlane_b32 s22, v254, 33
	v_readlane_b32 s23, v254, 34
	s_waitcnt vmcnt(7)
	v_mul_f32_e32 v2, 0xbfb8aa3b, v2
	s_waitcnt vmcnt(4)
	ds_write2st64_b32 v46, v40, v2 offset0:4 offset1:5
	s_waitcnt vmcnt(2)
	ds_write2st64_b32 v46, v41, v42 offset1:1
	s_waitcnt vmcnt(0)
	ds_write2st64_b32 v46, v43, v44 offset0:2 offset1:3
	v_mul_f32_e32 v48, 0xbfb8aa3b, v51
	v_mul_f32_e32 v47, 0xbfb8aa3b, v50
	v_fma_f32 v49, v51, s2, -v48
	v_rndne_f32_e32 v50, v48
	v_fmac_f32_e32 v49, 0xb2a5705f, v51
	v_sub_f32_e32 v48, v48, v50
	v_add_f32_e32 v48, v48, v49
	v_cvt_i32_f32_e32 v50, v50
	v_exp_f32_e32 v48, v48
	v_cmp_nlt_f32_e32 vcc, s3, v51
	s_mov_b32 s2, 0x7f800000
	v_ldexp_f32 v2, v48, v50
	v_cndmask_b32_e32 v2, 0, v2, vcc
	v_cmp_ngt_f32_e32 vcc, s5, v51
	s_nop 1
	v_cndmask_b32_e32 v2, v94, v2, vcc
	v_add_f32_e32 v42, 1.0, v2
	v_add_f32_e32 v43, -1.0, v42
	v_frexp_mant_f32_e32 v44, v42
	v_cvt_f64_f32_e32 v[40:41], v42
	v_sub_f32_e32 v48, v43, v42
	v_frexp_exp_i32_f64_e32 v40, v[40:41]
	v_cmp_gt_f32_e32 vcc, s9, v44
	v_sub_f32_e32 v43, v2, v43
	v_add_f32_e32 v41, 1.0, v48
	v_subbrev_co_u32_e32 v40, vcc, 0, v40, vcc
	v_add_f32_e32 v41, v43, v41
	v_sub_u32_e32 v43, 0, v40
	v_cvt_f32_i32_e32 v40, v40
	v_ldexp_f32 v42, v42, v43
	v_ldexp_f32 v41, v41, v43
	v_add_f32_e32 v43, -1.0, v42
	v_add_f32_e32 v44, 1.0, v42
	v_add_f32_e32 v48, 1.0, v43
	v_add_f32_e32 v49, -1.0, v44
	v_sub_f32_e32 v48, v42, v48
	v_sub_f32_e32 v42, v42, v49
	v_mul_f32_e32 v49, 0x3f317218, v40
	v_add_f32_e32 v48, v41, v48
	v_add_f32_e32 v41, v41, v42
	v_fma_f32 v42, v40, s10, -v49
	v_add_f32_e32 v50, v43, v48
	v_add_f32_e32 v51, v44, v41
	v_fmac_f32_e32 v42, 0xb102e308, v40
	v_sub_f32_e32 v40, v43, v50
	v_sub_f32_e32 v43, v44, v51
	v_rcp_f32_e32 v44, v51
	v_add_f32_e32 v53, v49, v42
	v_add_f32_e32 v41, v41, v43
	v_sub_f32_e32 v43, v53, v49
	v_sub_f32_e32 v42, v42, v43
	v_mul_f32_e32 v43, v50, v44
	v_add_f32_e32 v40, v48, v40
	v_mul_f32_e32 v48, v51, v43
	v_fma_f32 v49, v43, v51, -v48
	v_fmac_f32_e32 v49, v43, v41
	v_add_f32_e32 v54, v48, v49
	v_sub_f32_e32 v55, v50, v54
	v_sub_f32_e32 v48, v54, v48
	v_sub_f32_e32 v50, v50, v55
	v_sub_f32_e32 v48, v48, v49
	v_sub_f32_e32 v49, v50, v54
	v_add_f32_e32 v40, v40, v49
	v_add_f32_e32 v40, v48, v40
	v_add_f32_e32 v48, v55, v40
	v_mul_f32_e32 v49, v44, v48
	v_sub_f32_e32 v50, v55, v48
	v_mul_f32_e32 v54, v51, v49
	v_add_f32_e32 v40, v40, v50
	v_add_f32_e32 v50, v43, v49
	v_fma_f32 v51, v49, v51, -v54
	v_sub_f32_e32 v43, v50, v43
	v_fmac_f32_e32 v51, v49, v41
	v_sub_f32_e32 v41, v49, v43
	v_add_f32_e32 v43, v54, v51
	v_sub_f32_e32 v49, v43, v54
	v_sub_f32_e32 v54, v48, v43
	v_sub_f32_e32 v48, v48, v54
	v_sub_f32_e32 v43, v48, v43
	v_sub_f32_e32 v49, v49, v51
	v_add_f32_e32 v40, v40, v43
	v_add_f32_e32 v40, v49, v40
	v_add_f32_e32 v40, v54, v40
	v_mul_f32_e32 v40, v44, v40
	v_add_f32_e32 v40, v41, v40
	v_add_f32_e32 v41, v50, v40
	v_mul_f32_e32 v43, v41, v41
	v_fmamk_f32 v49, v43, 0x3e9b6dac, v92
	v_sub_f32_e32 v44, v41, v50
	v_ldexp_f32 v48, v41, 1
	v_mul_f32_e32 v41, v41, v43
	v_fmaak_f32 v43, v43, v49, 0x3f2aaada
	v_mul_f32_e32 v41, v41, v43
	v_add_f32_e32 v43, v48, v41
	v_sub_f32_e32 v40, v40, v44
	v_sub_f32_e32 v44, v43, v48
	v_ldexp_f32 v40, v40, 1
	v_sub_f32_e32 v41, v41, v44
	v_add_f32_e32 v40, v40, v41
	v_add_f32_e32 v41, v43, v40
	v_sub_f32_e32 v43, v41, v43
	v_add_f32_e32 v44, v53, v41
	v_sub_f32_e32 v40, v40, v43
	v_sub_f32_e32 v43, v44, v53
	v_sub_f32_e32 v48, v44, v43
	v_sub_f32_e32 v41, v41, v43
	v_add_f32_e32 v43, v42, v40
	v_sub_f32_e32 v48, v53, v48
	v_sub_f32_e32 v49, v43, v42
	v_add_f32_e32 v41, v41, v48
	v_sub_f32_e32 v48, v43, v49
	v_sub_f32_e32 v40, v40, v49
	v_sub_f32_e32 v42, v42, v48
	v_add_f32_e32 v41, v43, v41
	v_add_f32_e32 v40, v40, v42
	v_add_f32_e32 v42, v44, v41
	v_sub_f32_e32 v43, v42, v44
	v_sub_f32_e32 v41, v41, v43
	v_add_f32_e32 v40, v40, v41
	v_add_f32_e32 v40, v42, v40
	v_cmp_neq_f32_e32 vcc, s2, v2
	s_mov_b32 s2, 0x33800000
	s_nop 0
	v_cndmask_b32_e32 v40, v94, v40, vcc
	v_cmp_lt_f32_e64 vcc, |v2|, s2
	s_nop 1
	v_cndmask_b32_e32 v2, v40, v2, vcc
	v_mul_f32_e32 v2, 0xc138aa3b, v2
	ds_write2st64_b32 v46, v47, v2 offset0:6 offset1:7
	v_add_u32_e32 v2, 0x20800, v45
	ds_write2st64_b32 v2, v3, v3 offset1:1
.LBB0_202:
	s_or_b64 exec, exec, s[0:1]
	v_readlane_b32 s12, v254, 23
	s_lshl_b32 s2, s30, 14
	v_readlane_b32 s18, v254, 29
	v_lshlrev_b32_e32 v40, 6, v1
	v_readlane_b32 s19, v254, 30
	s_add_u32 s0, s18, s2
	v_ashrrev_i32_e32 v41, 31, v40
	v_readlane_b32 s22, v254, 33
	s_addc_u32 s1, s19, 0
	v_lshlrev_b64 v[48:49], 2, v[40:41]
	v_readlane_b32 s23, v254, 34
	v_lshl_add_u64 v[40:41], s[0:1], 0, v[48:49]
	s_add_u32 s0, s22, s2
	v_lshlrev_b32_e32 v2, 2, v0
	s_addc_u32 s1, s23, 0
	v_lshl_add_u64 v[44:45], v[40:41], 0, v[2:3]
	v_lshl_add_u64 v[48:49], s[0:1], 0, v[48:49]

	s_nop 0

	v_lshl_add_u64 v[54:55], v[48:49], 0, v[2:3]

	s_nop 0

	v_mul_u32_u24_e32 v0, 0x90, v0
	v_lshlrev_b32_e32 v1, 1, v1
	s_movk_i32 s0, 0x480
	v_readlane_b32 s1, v254, 49
	v_cmp_gt_i32_e32 vcc, s0, v52
	v_readlane_b32 s13, v254, 24
	v_add3_u32 v0, s1, v0, v1
	v_readlane_b32 s14, v254, 25
	v_readlane_b32 s15, v254, 26
	v_readlane_b32 s16, v254, 27
	v_readlane_b32 s17, v254, 28
	v_readlane_b32 s20, v254, 31
	v_readlane_b32 s21, v254, 32
	v_readlane_b32 s24, v254, 35
	v_readlane_b32 s25, v254, 36
	v_readlane_b32 s26, v254, 37
	v_readlane_b32 s27, v254, 38
	s_waitcnt vmcnt(3)
	v_cvt_pk_bf16_f32 v1, v238, s0
	v_cvt_pk_bf16_f32 v2, v239, s0
	v_cvt_pk_bf16_f32 v40, v240, s0
	v_cvt_pk_bf16_f32 v41, v241, s0
	s_waitcnt vmcnt(2)
	v_cvt_pk_bf16_f32 v42, v242, s0
	v_cvt_pk_bf16_f32 v43, v243, s0
	v_cvt_pk_bf16_f32 v44, v244, s0
	v_cvt_pk_bf16_f32 v45, v245, s0
	ds_write_b16 v0, v1
	ds_write_b16 v0, v2 offset:144
	ds_write_b16 v0, v40 offset:288
	ds_write_b16 v0, v41 offset:432
	ds_write_b16 v0, v42 offset:576
	ds_write_b16 v0, v43 offset:720
	ds_write_b16 v0, v44 offset:864
	ds_write_b16 v0, v45 offset:1008
	s_waitcnt vmcnt(1)
	v_cvt_pk_bf16_f32 v1, v246, s0
	v_cvt_pk_bf16_f32 v2, v247, s0
	v_cvt_pk_bf16_f32 v40, v248, s0
	v_cvt_pk_bf16_f32 v41, v249, s0
	s_waitcnt vmcnt(0)
	v_cvt_pk_bf16_f32 v42, v250, s0
	v_cvt_pk_bf16_f32 v43, v251, s0
	v_cvt_pk_bf16_f32 v44, v252, s0
	v_cvt_pk_bf16_f32 v45, v253, s0
	ds_write_b16 v0, v1 offset:9216
	ds_write_b16 v0, v2 offset:9360
	ds_write_b16 v0, v40 offset:9504
	ds_write_b16 v0, v41 offset:9648
	ds_write_b16 v0, v42 offset:9792
	ds_write_b16 v0, v43 offset:9936
	ds_write_b16 v0, v44 offset:10080
	ds_write_b16 v0, v45 offset:10224
	s_and_saveexec_b64 s[0:1], vcc
	s_cbranch_execz .LBB0_207
	v_add_u32_e32 v0, 0xfffffe00, v52
	v_lshlrev_b32_e32 v1, 4, v52
	v_readlane_b32 s2, v254, 50
	v_mov_b32_e32 v40, v0
	s_nop 0
	v_add_u32_e32 v2, s2, v1
	s_mov_b64 s[2:3], 0

.LBB0_207:
	s_or_b64 exec, exec, s[0:1]
	s_ashr_i32 s29, s28, 31
	v_writelane_b32 v255, s30, 11
	s_lshl_b32 s0, s30, 2
	v_writelane_b32 v255, s28, 12
	s_lshl_b32 s38, s28, 11
	s_cmp_lt_u32 s4, 64
	v_mov_b32_e32 v0, s0
	v_writelane_b32 v255, s29, 13
	s_cselect_b64 s[0:1], -1, 0
	v_writelane_b32 v255, s0, 14
	s_waitcnt lgkmcnt(0)
	s_barrier
	s_mov_b32 s40, 0
	v_writelane_b32 v255, s1, 15
	s_and_b32 s0, s4, 0x3fffffc0
	s_lshl_b32 s0, s0, 2
	s_add_i32 s0, s0, 0
	s_add_i32 s0, s0, 0x1f800
	s_cmp_eq_u32 s8, 7
	v_writelane_b32 v255, s0, 16
	s_cselect_b64 s[0:1], -1, 0
	v_writelane_b32 v255, s0, 17
	s_mov_b64 s[54:55], 0
	s_nop 0
	v_writelane_b32 v255, s1, 18
	v_readlane_b32 s1, v254, 45
	v_readlane_b32 s0, v255, 9
	s_lshl_b32 s0, s0, 1
	s_add_u32 s44, s1, s0
	v_readlane_b32 s0, v254, 46
	s_addc_u32 s45, s0, 0
	s_cmp_lt_i32 s8, 0
	s_cselect_b64 s[80:81], -1, 0
	s_cmp_gt_i32 s8, 0
	s_cselect_b64 s[82:83], -1, 0
	s_cmp_gt_i32 s8, 1
	s_cselect_b64 s[84:85], -1, 0
	s_cmp_gt_i32 s8, 2
	s_cselect_b64 s[86:87], -1, 0
	s_cmp_gt_i32 s8, 3
	s_cselect_b64 s[88:89], -1, 0
	s_cmp_gt_i32 s8, 4
	s_cselect_b64 s[90:91], -1, 0
	s_cmp_gt_i32 s8, 5
	s_cselect_b64 s[92:93], -1, 0
	s_cmp_gt_i32 s8, 6
	s_cselect_b64 s[94:95], -1, 0
	s_cmp_lt_i32 s8, 8
	s_cselect_b64 s[0:1], -1, 0
	s_and_b32 s79, s34, 0x70
	s_cmp_lt_i32 s8, 7
	v_writelane_b32 v255, s0, 19
	s_cselect_b64 s[98:99], -1, 0
	s_add_i32 s71, s34, 16
	v_writelane_b32 v255, s1, 20
	s_and_b32 s77, s71, 0x70
	s_add_i32 s0, s8, 2
	s_cmp_lt_i32 s8, 6
	s_cselect_b64 s[4:5], -1, 0
	s_lshl_b32 s74, s0, 4
	s_and_b32 s36, s74, 0x70
	s_cmp_lt_i32 s8, 5
	s_cselect_b64 s[26:27], -1, 0
	s_add_i32 s37, s34, 48
	s_and_b32 s72, s37, 0x70
	s_add_i32 s1, s8, 4
	s_cmp_lt_i32 s8, 4
	s_cselect_b64 s[24:25], -1, 0
	s_lshl_b32 s42, s1, 4
	s_and_b32 s43, s42, 0x70
	s_cmp_lt_i32 s8, 3
	s_cselect_b64 s[28:29], -1, 0
	s_add_i32 s46, s34, 0x50
	s_and_b32 s47, s46, 0x70
	s_add_i32 s9, s8, 6
	s_cmp_lt_i32 s8, 2
	s_cselect_b64 s[2:3], -1, 0
	s_lshl_b32 s48, s9, 4
	s_and_b32 s49, s48, 0x70
	s_cmp_lt_i32 s8, 1
	s_cselect_b64 s[30:31], -1, 0
	s_min_i32 s0, s0, 14
	s_lshl_b32 s0, s0, 4
	s_add_i32 s0, s0, 16
	s_and_b32 s51, s0, 0x70
	s_min_i32 s0, s1, 14
	s_lshl_b32 s0, s0, 4
	s_add_i32 s0, s0, 16
	s_and_b32 s33, s0, 0x70
	s_min_i32 s0, s9, 14
	s_lshl_b32 s0, s0, 4
	s_min_i32 s10, s8, 14
	s_add_i32 s0, s0, 16
	s_lshl_b32 s10, s10, 4
	s_and_b32 s35, s0, 0x70
	s_add_i32 s0, s8, 8
	s_add_i32 s10, s10, 16
	s_lshl_b32 s67, s0, 4
	s_add_i32 s62, s34, 0x70
	s_and_b32 s50, s10, 0x70
	s_min_i32 s0, s0, 14
	s_and_b32 s76, s62, 0x70
	s_and_b32 s73, s67, 0x70
	s_cmp_lt_i32 s8, -1
	v_readlane_b32 s8, v254, 23
	v_readlane_b32 s9, v254, 24
	v_readlane_b32 s10, v254, 25
	v_readlane_b32 s11, v254, 26
	v_readlane_b32 s12, v254, 27
	v_readlane_b32 s13, v254, 28
	v_readlane_b32 s14, v254, 29

	v_readlane_b32 s15, v254, 30
	v_readlane_b32 s16, v254, 31
	v_readlane_b32 s17, v254, 32
	v_readlane_b32 s18, v254, 33
	v_readlane_b32 s19, v254, 34
	v_readlane_b32 s20, v254, 35
	v_readlane_b32 s21, v254, 36
	v_readlane_b32 s22, v254, 37
	v_readlane_b32 s23, v254, 38
	v_writelane_b32 v255, s38, 21
	v_readlane_b32 s8, v254, 53
	s_cselect_b64 s[52:53], -1, 0
	s_lshl_b32 s0, s0, 4
	v_readlane_b32 s16, v254, 61
	v_readlane_b32 s17, v254, 62
	v_readlane_b32 s18, v254, 63
	v_readlane_b32 s19, v255, 0
	v_readlane_b32 s20, v255, 1
	v_readlane_b32 s21, v255, 2
	s_add_i32 s0, s0, 16
	v_readlane_b32 s22, v255, 3
	v_readlane_b32 s23, v255, 4
	s_mov_b64 s[16:17], s[20:21]
	s_and_b32 s75, s0, 0x70
	s_add_i32 s38, s38, s34
	s_mov_b64 s[18:19], s[22:23]
	s_add_u32 s39, s18, s7
	s_addc_u32 s78, s19, s6
	v_readlane_b32 s9, v254, 54
	v_readlane_b32 s10, v254, 55
	v_readlane_b32 s11, v254, 56
	v_readlane_b32 s12, v254, 57
	v_readlane_b32 s13, v254, 58
	v_readlane_b32 s14, v254, 59
	v_readlane_b32 s15, v254, 60
	s_waitcnt vmcnt(0)
	v_mul_f32_e32 v53, 0x3fb8aa3b, v236
	s_branch .LBB0_209
